# stack12 + nt streaming policy on part of the norm/weight-conversion phase's loads (those without an immediate offset)
# speedup vs baseline: 1.0041x; 1.0028x over previous
.LBB8_90:
	v_add_co_u32_e64 v38, s[0:1], s28, v122
	v_add_co_u32_e32 v36, vcc, s11, v122
	s_nop 0
	v_addc_co_u32_e64 v39, s[0:1], -1, v123, s[0:1]
	v_add_co_u32_e64 v40, s[0:1], s29, v122
	v_addc_co_u32_e32 v37, vcc, -1, v123, vcc
	s_nop 0
	v_addc_co_u32_e64 v41, s[0:1], -1, v123, s[0:1]
	global_load_dwordx4 v[16:19], v[122:123], off offset:-4096
	global_load_dwordx4 v[0:3], v[122:123], off offset:-3072
	global_load_dwordx4 v[4:7], v[122:123], off offset:-2048
	global_load_dwordx4 v[8:11], v[122:123], off offset:-1024
	global_load_dwordx4 v[12:15], v[122:123], off nt
	global_load_dwordx4 v[20:23], v[94:95], off nt
	global_load_dwordx4 v[32:35], v[94:95], off offset:1024
	global_load_dwordx4 v[28:31], v[94:95], off offset:2048
	global_load_dwordx4 v[24:27], v[94:95], off offset:3072
	global_load_dwordx4 v[72:75], v[38:39], off offset:-4096
	global_load_dwordx4 v[68:71], v[38:39], off offset:-3072
	global_load_dwordx4 v[60:63], v[38:39], off offset:-2048
	global_load_dwordx4 v[56:59], v[38:39], off offset:-1024
	global_load_dwordx4 v[52:55], v[38:39], off nt
	global_load_dwordx4 v[48:51], v[40:41], off offset:-2048
	global_load_dwordx4 v[44:47], v[40:41], off offset:-1024
	global_load_dwordx4 v[84:87], v[36:37], off offset:-3072
	global_load_dwordx4 v[80:83], v[36:37], off offset:-2048
	global_load_dwordx4 v[76:79], v[36:37], off offset:-1024
	global_load_dwordx4 v[64:67], v[40:41], off offset:-3072
	v_add_co_u32_e64 v124, s[0:1], s54, v120
	s_ashr_i32 s61, s60, 31
	s_nop 0
	v_addc_co_u32_e64 v125, s[0:1], 0, v121, s[0:1]
	s_lshr_b32 s0, s61, 21
	s_add_i32 s0, s60, s0
	s_lshr_b32 s0, s0, 11
	s_mulk_i32 s0, 0x6000
	s_ashr_i32 s1, s0, 31
	s_lshl_b64 s[0:1], s[0:1], 2
	s_add_u32 s0, s26, s0
	s_addc_u32 s1, s27, s1
	v_lshl_add_u64 v[140:141], v[92:93], 2, s[0:1]
	v_add_co_u32_e32 v132, vcc, s35, v140
	v_lshl_add_u64 v[138:139], v[140:141], 0, s[16:17]
	s_nop 0
	v_addc_co_u32_e32 v133, vcc, 0, v141, vcc
	v_add_co_u32_e32 v134, vcc, s54, v140
	global_load_dwordx4 v[40:43], v[140:141], off nt
	global_load_dwordx4 v[36:39], v[140:141], off offset:1024
	v_addc_co_u32_e32 v135, vcc, 0, v141, vcc
	v_add_co_u32_e32 v126, vcc, s55, v140
	s_add_i32 s60, s60, s8
	s_nop 0
	v_addc_co_u32_e32 v127, vcc, 0, v141, vcc
	v_add_co_u32_e32 v128, vcc, s9, v140
	v_lshl_add_u64 v[122:123], v[122:123], 0, s[14:15]
	s_nop 0
	v_addc_co_u32_e32 v129, vcc, 0, v141, vcc
	v_add_co_u32_e32 v130, vcc, s56, v140
	s_cmpk_gt_i32 s60, 0x1fff
	s_nop 0
	v_addc_co_u32_e32 v131, vcc, 0, v141, vcc
	v_add_co_u32_e32 v136, vcc, s57, v140
	s_waitcnt vmcnt(21)
	v_mul_f32_e32 v151, v17, v17
	v_mul_f32_e32 v168, v19, v19
	s_waitcnt vmcnt(20)
	v_mul_f32_e32 v169, v1, v1
	v_mul_f32_e32 v170, v3, v3
	s_waitcnt vmcnt(19)
	v_mul_f32_e32 v171, v5, v5
	v_mul_f32_e32 v172, v7, v7
	s_waitcnt vmcnt(18)
	v_mul_f32_e32 v173, v9, v9
	v_mul_f32_e32 v174, v11, v11
	s_waitcnt vmcnt(17)
	v_mul_f32_e32 v175, v13, v13
	v_mul_f32_e32 v176, v15, v15
	v_fmac_f32_e32 v151, v16, v16
	v_fmac_f32_e32 v168, v18, v18
	v_fmac_f32_e32 v169, v0, v0
	v_fmac_f32_e32 v170, v2, v2
	v_fmac_f32_e32 v171, v4, v4
	v_fmac_f32_e32 v172, v6, v6
	v_fmac_f32_e32 v173, v8, v8
	v_fmac_f32_e32 v174, v10, v10
	v_fmac_f32_e32 v175, v12, v12
	v_fmac_f32_e32 v176, v14, v14
	v_add_f32_e32 v151, v151, v168
	v_add_f32_e32 v168, v169, v170
	v_add_f32_e32 v169, v171, v172
	v_add_f32_e32 v170, v173, v174
	v_add_f32_e32 v171, v175, v176
	s_waitcnt vmcnt(5)
	v_mul_f32_e32 v172, v85, v85
	v_mul_f32_e32 v173, v87, v87
	s_waitcnt vmcnt(4)
	v_mul_f32_e32 v174, v81, v81
	v_mul_f32_e32 v175, v83, v83
	s_waitcnt vmcnt(3)
	v_mul_f32_e32 v176, v77, v77
	v_mul_f32_e32 v191, v79, v79
	v_fmac_f32_e32 v172, v84, v84
	v_fmac_f32_e32 v173, v86, v86
	v_fmac_f32_e32 v174, v80, v80
	v_fmac_f32_e32 v175, v82, v82
	v_mul_f32_e32 v177, v73, v73
	v_mul_f32_e32 v178, v75, v75
	v_fmac_f32_e32 v176, v76, v76
	v_fmac_f32_e32 v191, v78, v78
	v_add_f32_e32 v172, v172, v173
	v_add_f32_e32 v173, v174, v175
	v_mul_f32_e32 v179, v69, v69
	v_mul_f32_e32 v180, v71, v71
	v_fmac_f32_e32 v177, v72, v72
	v_fmac_f32_e32 v178, v74, v74
	v_add_f32_e32 v174, v176, v191
	v_add_f32_e32 v172, v172, v173
	v_mul_f32_e32 v181, v61, v61
	v_mul_f32_e32 v182, v63, v63
	v_fmac_f32_e32 v179, v68, v68
	v_fmac_f32_e32 v180, v70, v70
	v_add_f32_e32 v177, v177, v178
	v_add_f32_e32 v172, v172, v174
	v_addc_co_u32_e32 v137, vcc, 0, v141, vcc
	global_load_dwordx4 v[88:91], v[140:141], off offset:2048
	global_load_dwordx4 v[152:155], v[140:141], off offset:3072
	global_load_dwordx4 v[156:159], v[132:133], off offset:-4096
	global_load_dwordx4 v[160:163], v[138:139], off offset:1024
	global_load_dwordx4 v[164:167], v[138:139], off offset:2048
	s_nop 0
	global_load_dwordx4 v[138:141], v[138:139], off offset:3072
	v_mul_f32_e32 v183, v57, v57
	v_mul_f32_e32 v184, v59, v59
	v_fmac_f32_e32 v181, v60, v60
	v_fmac_f32_e32 v182, v62, v62
	v_add_f32_e32 v178, v179, v180
	v_add_f32_e32 v172, v172, v177
	v_mul_f32_e32 v185, v53, v53
	v_mul_f32_e32 v186, v55, v55
	v_fmac_f32_e32 v183, v56, v56
	v_fmac_f32_e32 v184, v58, v58
	v_add_f32_e32 v179, v181, v182
	v_add_f32_e32 v172, v172, v178
	v_fmac_f32_e32 v185, v52, v52
	v_fmac_f32_e32 v186, v54, v54
	s_waitcnt vmcnt(8)
	v_mul_f32_e32 v192, v65, v65
	v_mul_f32_e32 v193, v67, v67
	v_add_f32_e32 v180, v183, v184
	v_add_f32_e32 v172, v172, v179
	v_mul_f32_e32 v187, v49, v49
	v_mul_f32_e32 v188, v51, v51
	v_add_f32_e32 v181, v185, v186
	v_fmac_f32_e32 v192, v64, v64
	v_fmac_f32_e32 v193, v66, v66
	v_add_f32_e32 v172, v172, v180
	v_mul_f32_e32 v189, v45, v45
	v_mul_f32_e32 v190, v47, v47
	v_fmac_f32_e32 v187, v48, v48
	v_fmac_f32_e32 v188, v50, v50
	v_add_f32_e32 v175, v192, v193
	v_add_f32_e32 v172, v172, v181
	v_fmac_f32_e32 v189, v44, v44
	v_fmac_f32_e32 v190, v46, v46
	v_add_f32_e32 v182, v187, v188
	v_add_f32_e32 v172, v172, v175
	v_add_f32_e32 v183, v189, v190
	v_add_f32_e32 v172, v172, v182
	v_add_f32_e32 v172, v172, v183
	v_add_f32_e32 v151, v172, v151
	v_add_f32_e32 v151, v151, v168
	v_add_f32_e32 v151, v151, v169
	v_add_f32_e32 v151, v151, v170
	v_add_f32_e32 v151, v151, v171
	ds_bpermute_b32 v168, v143, v151
	s_waitcnt lgkmcnt(0)
	v_add_f32_e32 v151, v151, v168
	ds_bpermute_b32 v168, v144, v151
	s_waitcnt lgkmcnt(0)
	v_add_f32_e32 v151, v151, v168
	ds_bpermute_b32 v168, v145, v151
	s_waitcnt lgkmcnt(0)
	v_add_f32_e32 v151, v151, v168
	ds_bpermute_b32 v168, v146, v151
	s_waitcnt lgkmcnt(0)
	v_add_f32_e32 v151, v151, v168
	ds_bpermute_b32 v168, v147, v151
	s_waitcnt lgkmcnt(0)
	v_add_f32_e32 v151, v151, v168
	ds_bpermute_b32 v168, v148, v151
	s_waitcnt vmcnt(3)
	v_add_f32_e32 v156, 1.0, v156
	s_waitcnt lgkmcnt(0)
	v_add_f32_e32 v151, v151, v168
	v_fmamk_f32 v151, v151, 0x39800000, v149
	v_mul_f32_e32 v168, 0x4f800000, v151
	v_cmp_gt_f32_e32 vcc, s34, v151
	v_add_f32_e32 v157, 1.0, v157
	v_add_f32_e32 v158, 1.0, v158
	v_cndmask_b32_e32 v151, v151, v168, vcc
	v_sqrt_f32_e32 v168, v151
	v_add_f32_e32 v159, 1.0, v159
	s_waitcnt vmcnt(2)
	v_add_f32_e32 v160, 1.0, v160
	v_add_f32_e32 v161, 1.0, v161
	v_add_u32_e32 v169, -1, v168
	v_add_u32_e32 v170, 1, v168
	v_fma_f32 v171, -v169, v168, v151
	v_fma_f32 v172, -v170, v168, v151
	v_cmp_ge_f32_e64 s[0:1], 0, v171
	v_add_f32_e32 v162, 1.0, v162
	v_add_f32_e32 v163, 1.0, v163
	v_cndmask_b32_e64 v168, v168, v169, s[0:1]
	v_cmp_lt_f32_e64 s[0:1], 0, v172
	s_waitcnt vmcnt(1)
	v_add_f32_e32 v164, 1.0, v164
	v_add_f32_e32 v165, 1.0, v165
	v_cndmask_b32_e64 v168, v168, v170, s[0:1]
	v_mul_f32_e32 v169, 0x37800000, v168
	v_cndmask_b32_e32 v168, v168, v169, vcc
	v_cmp_class_f32_e32 vcc, v151, v150
	v_add_f32_e32 v166, 1.0, v166
	v_add_f32_e32 v167, 1.0, v167
	v_cndmask_b32_e32 v151, v168, v151, vcc
	v_div_scale_f32 v168, s[0:1], v151, v151, 1.0
	v_rcp_f32_e32 v170, v168
	v_div_scale_f32 v169, vcc, 1.0, v151, 1.0
	s_waitcnt vmcnt(0)
	v_add_f32_e32 v138, 1.0, v138
	v_fma_f32 v171, -v168, v170, 1.0
	v_fmac_f32_e32 v170, v171, v170
	v_mul_f32_e32 v171, v169, v170
	v_fma_f32 v172, -v168, v171, v169
	v_fmac_f32_e32 v171, v172, v170
	v_fma_f32 v168, -v168, v171, v169
	v_div_fmas_f32 v168, v168, v170, v171
	v_div_fixup_f32 v151, v168, v151, 1.0
	v_mul_f32_e32 v84, v84, v151
	v_mul_f32_e32 v85, v85, v151
	v_mul_f32_e32 v86, v86, v151
	v_mul_f32_e32 v87, v87, v151
	v_mul_f32_e32 v80, v80, v151
	v_mul_f32_e32 v81, v81, v151
	v_mul_f32_e32 v82, v82, v151
	v_mul_f32_e32 v83, v83, v151
	v_mul_f32_e32 v76, v76, v151
	v_mul_f32_e32 v77, v77, v151
	v_mul_f32_e32 v188, v16, v151
	v_mul_f32_e32 v189, v17, v151
	v_mul_f32_e32 v16, v20, v84
	v_mul_f32_e32 v17, v21, v85
	v_mul_f32_e32 v78, v78, v151
	v_mul_f32_e32 v79, v79, v151
	v_mul_f32_e32 v72, v72, v151
	v_mul_f32_e32 v73, v73, v151
	v_mul_f32_e32 v74, v74, v151
	v_mul_f32_e32 v75, v75, v151
	v_mul_f32_e32 v190, v18, v151
	v_mul_f32_e32 v191, v19, v151
	v_mul_f32_e32 v18, v22, v86
	v_mul_f32_e32 v19, v23, v87
	v_mul_f32_e32 v20, v32, v80
	v_mul_f32_e32 v21, v33, v81
	v_mul_f32_e32 v22, v34, v82
	v_mul_f32_e32 v23, v35, v83
	v_mul_f32_e32 v28, v28, v76
	v_mul_f32_e32 v29, v29, v77
	v_fma_f32 v16, v156, v16, v40
	v_fma_f32 v17, v157, v17, v41
	v_add_f32_e32 v139, 1.0, v139
	v_add_f32_e32 v140, 1.0, v140
	v_add_f32_e32 v141, 1.0, v141
	v_mul_f32_e32 v30, v30, v78
	v_mul_f32_e32 v31, v31, v79
	v_mul_f32_e32 v24, v72, v24
	v_mul_f32_e32 v25, v73, v25
	v_mul_f32_e32 v26, v74, v26
	v_mul_f32_e32 v27, v75, v27
	v_fma_f32 v18, v158, v18, v42
	v_fmac_f32_e32 v43, v159, v19
	v_fma_f32 v19, v160, v20, v36
	v_fma_f32 v20, v161, v21, v37
	v_fma_f32 v21, v162, v22, v38
	v_fmac_f32_e32 v39, v163, v23
	v_fma_f32 v22, v28, v164, v88
	v_fma_f32 v23, v29, v165, v89
	v_cvt_pk_bf16_f32 v16, v16, v17
	v_cvt_pk_bf16_f32 v17, v18, v43
	v_fma_f32 v28, v30, v166, v90
	v_fmac_f32_e32 v91, v31, v167
	v_fma_f32 v24, v24, v138, v152
	v_fma_f32 v25, v25, v139, v153
	v_fma_f32 v26, v26, v140, v154
	v_fmac_f32_e32 v155, v27, v141
	v_cvt_pk_bf16_f32 v18, v19, v20
	v_cvt_pk_bf16_f32 v19, v21, v39
	v_cvt_pk_bf16_f32 v20, v22, v23
	v_cvt_pk_bf16_f32 v21, v28, v91
	v_cvt_pk_bf16_f32 v22, v24, v25
	v_cvt_pk_bf16_f32 v23, v26, v155
	global_store_dwordx2 v[120:121], v[16:17], off
	global_store_dwordx2 v[120:121], v[18:19], off offset:512
	global_store_dwordx2 v[120:121], v[20:21], off offset:1024
	global_store_dwordx2 v[120:121], v[22:23], off offset:1536
	v_mul_f32_e32 v168, v60, v151
	v_mul_f32_e32 v169, v61, v151
	v_mul_f32_e32 v170, v62, v151
	v_mul_f32_e32 v171, v63, v151
	v_mul_f32_e32 v172, v56, v151
	v_mul_f32_e32 v173, v57, v151
	v_mul_f32_e32 v174, v58, v151
	v_mul_f32_e32 v175, v59, v151
	v_mul_f32_e32 v176, v52, v151
	v_mul_f32_e32 v177, v53, v151
	v_mul_f32_e32 v178, v54, v151
	v_mul_f32_e32 v179, v55, v151
	v_mul_f32_e32 v180, v48, v151
	v_mul_f32_e32 v181, v49, v151
	v_mul_f32_e32 v182, v50, v151
	v_mul_f32_e32 v183, v51, v151
	v_mul_f32_e32 v184, v44, v151
	v_mul_f32_e32 v185, v45, v151
	v_mul_f32_e32 v186, v46, v151
	v_mul_f32_e32 v187, v47, v151
	global_load_dwordx4 v[16:19], v[96:97], off nt
	global_load_dwordx4 v[20:23], v[132:133], off nt
	global_load_dwordx4 v[24:27], v[98:99], off nt
	global_load_dwordx4 v[28:31], v[132:133], off offset:1024
	global_load_dwordx4 v[32:35], v[100:101], off nt
	global_load_dwordx4 v[36:39], v[132:133], off offset:2048
	global_load_dwordx4 v[40:43], v[102:103], off nt
	global_load_dwordx4 v[44:47], v[132:133], off offset:3072
	global_load_dwordx4 v[48:51], v[126:127], off offset:-4096
	global_load_dwordx4 v[52:55], v[134:135], off offset:1024
	global_load_dwordx4 v[56:59], v[134:135], off offset:2048
	global_load_dwordx4 v[60:63], v[134:135], off offset:3072
	v_mul_f32_e32 v68, v68, v151
	v_mul_f32_e32 v69, v69, v151
	v_mul_f32_e32 v70, v70, v151
	v_mul_f32_e32 v71, v71, v151
	v_mul_f32_e32 v64, v64, v151
	v_mul_f32_e32 v65, v65, v151
	v_mul_f32_e32 v66, v66, v151
	v_mul_f32_e32 v67, v67, v151
	v_mul_f32_e32 v0, v0, v151
	v_mul_f32_e32 v1, v1, v151
	v_mul_f32_e32 v2, v2, v151
	v_mul_f32_e32 v3, v3, v151
	v_mul_f32_e32 v4, v4, v151
	v_mul_f32_e32 v5, v5, v151
	v_mul_f32_e32 v6, v6, v151
	v_mul_f32_e32 v7, v7, v151
	v_mul_f32_e32 v8, v8, v151
	v_mul_f32_e32 v9, v9, v151
	v_mul_f32_e32 v10, v10, v151
	v_mul_f32_e32 v11, v11, v151
	v_mul_f32_e32 v12, v12, v151
	v_mul_f32_e32 v13, v13, v151
	v_mul_f32_e32 v14, v14, v151
	v_mul_f32_e32 v15, v15, v151
	s_waitcnt vmcnt(11)
	v_mul_f32_e32 v16, v68, v16
	s_waitcnt vmcnt(10)
	v_add_f32_e32 v20, 1.0, v20
	v_mul_f32_e32 v17, v69, v17
	v_add_f32_e32 v21, 1.0, v21
	v_mul_f32_e32 v18, v70, v18
	v_add_f32_e32 v22, 1.0, v22
	v_mul_f32_e32 v19, v71, v19
	v_add_f32_e32 v23, 1.0, v23
	s_waitcnt vmcnt(9)
	v_mul_f32_e32 v24, v168, v24
	s_waitcnt vmcnt(8)
	v_add_f32_e32 v28, 1.0, v28
	v_mul_f32_e32 v25, v169, v25
	v_add_f32_e32 v29, 1.0, v29
	v_mul_f32_e32 v26, v170, v26
	v_add_f32_e32 v30, 1.0, v30
	s_waitcnt vmcnt(7)
	v_mul_f32_e32 v32, v172, v32
	s_waitcnt vmcnt(6)
	v_add_f32_e32 v36, 1.0, v36
	v_mul_f32_e32 v33, v173, v33
	v_add_f32_e32 v37, 1.0, v37
	s_waitcnt vmcnt(3)
	v_fma_f32 v16, v16, v20, v48
	v_fma_f32 v17, v17, v21, v49
	v_mul_f32_e32 v27, v171, v27
	v_add_f32_e32 v31, 1.0, v31
	v_mul_f32_e32 v34, v174, v34
	v_add_f32_e32 v38, 1.0, v38
	v_mul_f32_e32 v35, v175, v35
	v_add_f32_e32 v39, 1.0, v39
	v_mul_f32_e32 v40, v176, v40
	v_add_f32_e32 v44, 1.0, v44
	v_mul_f32_e32 v41, v177, v41
	v_add_f32_e32 v45, 1.0, v45
	v_mul_f32_e32 v42, v178, v42
	v_add_f32_e32 v46, 1.0, v46
	v_mul_f32_e32 v43, v179, v43
	v_add_f32_e32 v47, 1.0, v47
	v_fma_f32 v18, v18, v22, v50
	v_fmac_f32_e32 v51, v19, v23
	s_waitcnt vmcnt(2)
	v_fma_f32 v19, v24, v28, v52
	v_fma_f32 v20, v25, v29, v53
	v_fma_f32 v21, v26, v30, v54
	s_waitcnt vmcnt(1)
	v_fma_f32 v22, v32, v36, v56
	v_fma_f32 v23, v33, v37, v57
	v_cvt_pk_bf16_f32 v16, v16, v17
	v_cvt_pk_bf16_f32 v17, v18, v51
	v_fmac_f32_e32 v55, v27, v31
	v_fma_f32 v24, v34, v38, v58
	v_fmac_f32_e32 v59, v35, v39
	s_waitcnt vmcnt(0)
	v_fma_f32 v25, v40, v44, v60
	v_fma_f32 v26, v41, v45, v61
	v_fma_f32 v27, v42, v46, v62
	v_fmac_f32_e32 v63, v43, v47
	v_cvt_pk_bf16_f32 v18, v19, v20
	v_cvt_pk_bf16_f32 v19, v21, v55
	v_cvt_pk_bf16_f32 v20, v22, v23
	v_cvt_pk_bf16_f32 v21, v24, v59
	v_cvt_pk_bf16_f32 v22, v25, v26
	v_cvt_pk_bf16_f32 v23, v27, v63
	global_store_dwordx2 v[120:121], v[16:17], off offset:2048
	global_store_dwordx2 v[120:121], v[18:19], off offset:2560
	global_store_dwordx2 v[120:121], v[20:21], off offset:3072
	global_store_dwordx2 v[120:121], v[22:23], off offset:3584
	global_load_dwordx4 v[16:19], v[104:105], off nt
	s_nop 0
	global_load_dwordx4 v[20:23], v[130:131], off offset:-4096
	global_load_dwordx4 v[24:27], v[106:107], off nt
	global_load_dwordx4 v[28:31], v[128:129], off offset:1024
	global_load_dwordx4 v[32:35], v[108:109], off nt
	global_load_dwordx4 v[36:39], v[128:129], off offset:2048
	global_load_dwordx4 v[40:43], v[110:111], off nt
	global_load_dwordx4 v[44:47], v[128:129], off offset:3072
	global_load_dwordx4 v[48:51], v[126:127], off nt
	global_load_dwordx4 v[52:55], v[126:127], off offset:1024
	global_load_dwordx4 v[56:59], v[126:127], off offset:2048
	global_load_dwordx4 v[60:63], v[126:127], off offset:3072
	v_lshl_add_u64 v[120:121], v[120:121], 0, s[12:13]
	s_waitcnt vmcnt(11)
	v_mul_f32_e32 v16, v64, v16
	s_waitcnt vmcnt(10)
	v_add_f32_e32 v20, 1.0, v20
	v_mul_f32_e32 v17, v65, v17
	v_add_f32_e32 v21, 1.0, v21
	v_mul_f32_e32 v18, v66, v18
	v_add_f32_e32 v22, 1.0, v22
	v_mul_f32_e32 v19, v67, v19
	v_add_f32_e32 v23, 1.0, v23
	s_waitcnt vmcnt(9)
	v_mul_f32_e32 v24, v180, v24
	s_waitcnt vmcnt(8)
	v_add_f32_e32 v28, 1.0, v28
	v_mul_f32_e32 v25, v181, v25
	v_add_f32_e32 v29, 1.0, v29
	v_mul_f32_e32 v26, v182, v26
	v_add_f32_e32 v30, 1.0, v30
	s_waitcnt vmcnt(7)
	v_mul_f32_e32 v32, v184, v32
	s_waitcnt vmcnt(6)
	v_add_f32_e32 v36, 1.0, v36
	v_mul_f32_e32 v33, v185, v33
	v_add_f32_e32 v37, 1.0, v37
	s_waitcnt vmcnt(3)
	v_fma_f32 v16, v16, v20, v48
	v_fma_f32 v17, v17, v21, v49
	v_mul_f32_e32 v27, v183, v27
	v_add_f32_e32 v31, 1.0, v31
	v_mul_f32_e32 v34, v186, v34
	v_add_f32_e32 v38, 1.0, v38
	v_mul_f32_e32 v35, v187, v35
	v_add_f32_e32 v39, 1.0, v39
	v_mul_f32_e32 v40, v188, v40
	v_add_f32_e32 v44, 1.0, v44
	v_mul_f32_e32 v41, v189, v41
	v_add_f32_e32 v45, 1.0, v45
	v_mul_f32_e32 v42, v190, v42
	v_add_f32_e32 v46, 1.0, v46
	v_mul_f32_e32 v43, v191, v43
	v_add_f32_e32 v47, 1.0, v47
	v_fma_f32 v18, v18, v22, v50
	v_fmac_f32_e32 v51, v19, v23
	s_waitcnt vmcnt(2)
	v_fma_f32 v19, v24, v28, v52
	v_fma_f32 v20, v25, v29, v53
	v_fma_f32 v21, v26, v30, v54
	s_waitcnt vmcnt(1)
	v_fma_f32 v22, v32, v36, v56
	v_fma_f32 v23, v33, v37, v57
	v_cvt_pk_bf16_f32 v16, v16, v17
	v_cvt_pk_bf16_f32 v17, v18, v51
	v_fmac_f32_e32 v55, v27, v31
	v_fma_f32 v24, v34, v38, v58
	v_fmac_f32_e32 v59, v35, v39
	s_waitcnt vmcnt(0)
	v_fma_f32 v25, v40, v44, v60
	v_fma_f32 v26, v41, v45, v61
	v_fma_f32 v27, v42, v46, v62
	v_fmac_f32_e32 v63, v43, v47
	v_cvt_pk_bf16_f32 v18, v19, v20
	v_cvt_pk_bf16_f32 v19, v21, v55
	v_cvt_pk_bf16_f32 v20, v22, v23
	v_cvt_pk_bf16_f32 v21, v24, v59
	v_cvt_pk_bf16_f32 v22, v25, v26
	v_cvt_pk_bf16_f32 v23, v27, v63
	global_store_dwordx2 v[124:125], v[16:17], off
	global_store_dwordx2 v[124:125], v[18:19], off offset:512
	global_store_dwordx2 v[124:125], v[20:21], off offset:1024
	global_store_dwordx2 v[124:125], v[22:23], off offset:1536
	global_load_dwordx4 v[16:19], v[112:113], off nt
	s_nop 0
	global_load_dwordx4 v[20:23], v[130:131], off nt
	global_load_dwordx4 v[24:27], v[114:115], off nt
	global_load_dwordx4 v[28:31], v[130:131], off offset:1024
	global_load_dwordx4 v[32:35], v[116:117], off nt
	global_load_dwordx4 v[36:39], v[130:131], off offset:2048
	global_load_dwordx4 v[40:43], v[118:119], off nt
	global_load_dwordx4 v[44:47], v[130:131], off offset:3072
	global_load_dwordx4 v[48:51], v[136:137], off nt
	global_load_dwordx4 v[52:55], v[136:137], off offset:1024
	global_load_dwordx4 v[56:59], v[136:137], off offset:2048
	global_load_dwordx4 v[60:63], v[136:137], off offset:3072
	s_waitcnt vmcnt(11)
	v_mul_f32_e32 v0, v0, v16
	s_waitcnt vmcnt(10)
	v_add_f32_e32 v16, 1.0, v20
	v_mul_f32_e32 v1, v1, v17
	v_add_f32_e32 v17, 1.0, v21
	v_mul_f32_e32 v2, v2, v18
	v_add_f32_e32 v18, 1.0, v22
	v_mul_f32_e32 v3, v3, v19
	v_add_f32_e32 v19, 1.0, v23
	s_waitcnt vmcnt(9)
	v_mul_f32_e32 v4, v4, v24
	s_waitcnt vmcnt(8)
	v_add_f32_e32 v20, 1.0, v28
	v_mul_f32_e32 v5, v5, v25
	v_add_f32_e32 v21, 1.0, v29
	v_mul_f32_e32 v6, v6, v26
	v_add_f32_e32 v22, 1.0, v30
	v_mul_f32_e32 v7, v7, v27
	v_add_f32_e32 v23, 1.0, v31
	s_waitcnt vmcnt(7)
	v_mul_f32_e32 v8, v8, v32
	s_waitcnt vmcnt(6)
	v_add_f32_e32 v24, 1.0, v36
	v_mul_f32_e32 v9, v9, v33
	v_add_f32_e32 v25, 1.0, v37
	s_waitcnt vmcnt(3)
	v_fma_f32 v0, v0, v16, v48
	v_fma_f32 v1, v1, v17, v49
	v_mul_f32_e32 v10, v10, v34
	v_add_f32_e32 v26, 1.0, v38
	v_mul_f32_e32 v11, v11, v35
	v_add_f32_e32 v27, 1.0, v39
	v_mul_f32_e32 v12, v12, v40
	v_add_f32_e32 v28, 1.0, v44
	v_mul_f32_e32 v13, v13, v41
	v_add_f32_e32 v29, 1.0, v45
	v_mul_f32_e32 v14, v14, v42
	v_add_f32_e32 v30, 1.0, v46
	v_mul_f32_e32 v15, v15, v43
	v_add_f32_e32 v31, 1.0, v47
	v_fma_f32 v2, v2, v18, v50
	v_fmac_f32_e32 v51, v3, v19
	s_waitcnt vmcnt(2)
	v_fma_f32 v3, v4, v20, v52
	v_fma_f32 v4, v5, v21, v53
	v_fma_f32 v5, v6, v22, v54
	v_fmac_f32_e32 v55, v7, v23
	s_waitcnt vmcnt(1)
	v_fma_f32 v6, v8, v24, v56
	v_fma_f32 v7, v9, v25, v57
	v_cvt_pk_bf16_f32 v0, v0, v1
	v_cvt_pk_bf16_f32 v1, v2, v51
	v_fma_f32 v8, v10, v26, v58
	v_fmac_f32_e32 v59, v11, v27
	s_waitcnt vmcnt(0)
	v_fma_f32 v9, v12, v28, v60
	v_fma_f32 v10, v13, v29, v61
	v_fma_f32 v11, v14, v30, v62
	v_fmac_f32_e32 v63, v15, v31
	v_cvt_pk_bf16_f32 v2, v3, v4
	v_cvt_pk_bf16_f32 v3, v5, v55
	v_cvt_pk_bf16_f32 v4, v6, v7
	v_cvt_pk_bf16_f32 v5, v8, v59
	v_cvt_pk_bf16_f32 v6, v9, v10
	v_cvt_pk_bf16_f32 v7, v11, v63
	global_store_dwordx2 v[124:125], v[0:1], off offset:2048
	global_store_dwordx2 v[124:125], v[2:3], off offset:2560
	global_store_dwordx2 v[124:125], v[4:5], off offset:3072
	global_store_dwordx2 v[124:125], v[6:7], off offset:3584
	s_cbranch_scc0 .LBB8_90

.LBB8_108:
	v_ashrrev_i32_e32 v131, 3, v142
	v_and_b32_e32 v134, -2, v131
	v_lshl_add_u32 v30, v132, 6, v134
	v_add_u32_e32 v26, 25, v30
	s_ashr_i32 s17, s16, 31
	v_mad_i64_i32 v[26:27], s[28:29], s14, v26, 0
	v_and_b32_e32 v64, 60, v92
	s_lshl_b64 s[16:17], s[16:17], 2
	v_lshl_add_u64 v[26:27], v[26:27], 2, s[12:13]
	v_mov_b32_e32 v129, 0
	v_lshlrev_b32_e32 v128, 2, v64
	v_lshl_add_u64 v[26:27], v[26:27], 0, s[16:17]
	v_lshl_add_u64 v[28:29], v[26:27], 0, v[128:129]
	v_add_u32_e32 v26, 32, v30
	v_mad_i64_i32 v[26:27], s[28:29], s14, v26, 0
	v_lshl_add_u64 v[26:27], v[26:27], 2, s[12:13]
	v_lshl_add_u64 v[26:27], v[26:27], 0, s[16:17]
	v_lshl_add_u64 v[32:33], v[26:27], 0, v[128:129]
	v_add_u32_e32 v26, 33, v30
	v_mad_i64_i32 v[26:27], s[28:29], s14, v26, 0
	v_lshl_add_u64 v[26:27], v[26:27], 2, s[12:13]
	v_lshl_add_u64 v[26:27], v[26:27], 0, s[16:17]
	v_lshl_add_u64 v[36:37], v[26:27], 0, v[128:129]
	v_add_u32_e32 v26, 40, v30
	v_mad_i64_i32 v[26:27], s[28:29], s14, v26, 0
	v_lshl_add_u64 v[26:27], v[26:27], 2, s[12:13]
	v_lshl_add_u64 v[26:27], v[26:27], 0, s[16:17]
	v_lshl_add_u64 v[40:41], v[26:27], 0, v[128:129]
	v_add_u32_e32 v26, 41, v30
	v_mad_i64_i32 v[26:27], s[28:29], s14, v26, 0
	v_lshl_add_u64 v[26:27], v[26:27], 2, s[12:13]
	v_lshl_add_u64 v[26:27], v[26:27], 0, s[16:17]
	v_lshl_add_u64 v[44:45], v[26:27], 0, v[128:129]
	v_add_u32_e32 v26, 48, v30
	v_mad_i64_i32 v[26:27], s[28:29], s14, v26, 0
	v_lshl_add_u64 v[26:27], v[26:27], 2, s[12:13]
	v_lshl_add_u64 v[26:27], v[26:27], 0, s[16:17]
	v_lshl_add_u64 v[48:49], v[26:27], 0, v[128:129]
	v_add_u32_e32 v26, 49, v30
	v_mad_i64_i32 v[26:27], s[28:29], s14, v26, 0
	v_lshl_add_u64 v[26:27], v[26:27], 2, s[12:13]
	v_lshl_add_u64 v[26:27], v[26:27], 0, s[16:17]
	v_lshl_add_u64 v[52:53], v[26:27], 0, v[128:129]
	v_add_u32_e32 v26, 56, v30
	v_mad_i64_i32 v[26:27], s[28:29], s14, v26, 0
	v_lshl_add_u64 v[26:27], v[26:27], 2, s[12:13]
	v_lshl_add_u64 v[26:27], v[26:27], 0, s[16:17]
	v_or_b32_e32 v2, 1, v30
	v_add_u32_e32 v8, 8, v30
	v_add_u32_e32 v10, 9, v30
	v_add_u32_e32 v16, 16, v30
	v_add_u32_e32 v18, 17, v30
	v_add_u32_e32 v24, 24, v30
	v_lshl_add_u64 v[56:57], v[26:27], 0, v[128:129]
	v_add_u32_e32 v26, 57, v30
	v_mad_i64_i32 v[0:1], s[28:29], s14, v30, 0
	v_mad_i64_i32 v[2:3], s[28:29], s14, v2, 0
	v_mad_i64_i32 v[8:9], s[28:29], s14, v8, 0
	v_mad_i64_i32 v[10:11], s[28:29], s14, v10, 0
	v_mad_i64_i32 v[16:17], s[28:29], s14, v16, 0
	v_mad_i64_i32 v[18:19], s[28:29], s14, v18, 0
	v_mad_i64_i32 v[24:25], s[28:29], s14, v24, 0
	v_mad_i64_i32 v[26:27], s[14:15], s14, v26, 0
	v_lshl_add_u64 v[0:1], v[0:1], 2, s[12:13]
	v_lshl_add_u64 v[2:3], v[2:3], 2, s[12:13]
	v_lshl_add_u64 v[8:9], v[8:9], 2, s[12:13]
	v_lshl_add_u64 v[10:11], v[10:11], 2, s[12:13]
	v_lshl_add_u64 v[16:17], v[16:17], 2, s[12:13]
	v_lshl_add_u64 v[18:19], v[18:19], 2, s[12:13]
	v_lshl_add_u64 v[24:25], v[24:25], 2, s[12:13]
	v_lshl_add_u64 v[26:27], v[26:27], 2, s[12:13]
	v_lshl_add_u64 v[0:1], v[0:1], 0, s[16:17]
	v_lshl_add_u64 v[2:3], v[2:3], 0, s[16:17]
	v_lshl_add_u64 v[8:9], v[8:9], 0, s[16:17]
	v_lshl_add_u64 v[10:11], v[10:11], 0, s[16:17]
	v_lshl_add_u64 v[16:17], v[16:17], 0, s[16:17]
	v_lshl_add_u64 v[18:19], v[18:19], 0, s[16:17]
	v_lshl_add_u64 v[24:25], v[24:25], 0, s[16:17]
	v_lshl_add_u64 v[26:27], v[26:27], 0, s[16:17]
	v_lshl_add_u64 v[0:1], v[0:1], 0, v[128:129]
	v_lshl_add_u64 v[4:5], v[2:3], 0, v[128:129]
	v_lshl_add_u64 v[8:9], v[8:9], 0, v[128:129]
	v_lshl_add_u64 v[12:13], v[10:11], 0, v[128:129]
	v_lshl_add_u64 v[16:17], v[16:17], 0, v[128:129]
	v_lshl_add_u64 v[20:21], v[18:19], 0, v[128:129]
	v_lshl_add_u64 v[24:25], v[24:25], 0, v[128:129]
	v_lshl_add_u64 v[60:61], v[26:27], 0, v[128:129]
	global_load_dwordx4 v[0:3], v[0:1], off nt
	s_nop 0
	global_load_dwordx4 v[4:7], v[4:5], off nt
	s_nop 0
	global_load_dwordx4 v[8:11], v[8:9], off nt
	s_nop 0
	global_load_dwordx4 v[12:15], v[12:13], off nt
	s_nop 0
	global_load_dwordx4 v[16:19], v[16:17], off nt
	s_nop 0
	global_load_dwordx4 v[20:23], v[20:21], off nt
	s_nop 0
	global_load_dwordx4 v[24:27], v[24:25], off nt
	s_nop 0
	global_load_dwordx4 v[28:31], v[28:29], off nt
	s_nop 0
	global_load_dwordx4 v[32:35], v[32:33], off nt
	s_nop 0
	global_load_dwordx4 v[36:39], v[36:37], off nt
	s_nop 0
	global_load_dwordx4 v[40:43], v[40:41], off nt
	s_nop 0
	global_load_dwordx4 v[44:47], v[44:45], off nt
	s_nop 0
	global_load_dwordx4 v[48:51], v[48:49], off nt
	s_nop 0
	global_load_dwordx4 v[52:55], v[52:53], off nt
	s_nop 0
	global_load_dwordx4 v[56:59], v[56:57], off nt
	s_nop 0
	global_load_dwordx4 v[60:63], v[60:61], off nt
	v_readlane_b32 s11, v254, 4
	v_add_u32_e32 v135, 8, v131
	s_mulk_i32 s11, 0x4100
	v_bitop3_b32 v75, v135, 28, v92 bitop3:0x48
	s_add_i32 s11, s11, 0
	v_lshlrev_b32_e32 v74, 7, v135
	v_lshlrev_b32_e32 v75, 2, v75
	v_add_u32_e32 v137, 16, v131
	v_add3_u32 v136, s11, v74, v75
	v_bitop3_b32 v75, v137, 28, v92 bitop3:0x48
	v_lshlrev_b32_e32 v74, 7, v137
	v_lshlrev_b32_e32 v75, 2, v75
	v_add_u32_e32 v139, 24, v131
	v_add3_u32 v138, s11, v74, v75
	v_bitop3_b32 v75, v139, 28, v92 bitop3:0x48
	v_add_u32_e32 v143, 40, v131
	v_lshlrev_b32_e32 v74, 7, v139
	v_lshlrev_b32_e32 v75, 2, v75
	v_bitop3_b32 v76, v143, 28, v92 bitop3:0x48
	v_add3_u32 v140, s11, v74, v75
	v_lshlrev_b32_e32 v75, 7, v143
	v_lshlrev_b32_e32 v76, 2, v76
	v_add_u32_e32 v145, 48, v131
	v_add3_u32 v144, s11, v75, v76
	v_bitop3_b32 v76, v145, 28, v92 bitop3:0x48
	v_lshlrev_b32_e32 v75, 7, v145
	v_lshlrev_b32_e32 v76, 2, v76
	v_add_u32_e32 v147, 56, v131
	v_ashrrev_i32_e32 v65, 4, v142
	v_add3_u32 v146, s11, v75, v76
	v_bitop3_b32 v75, v147, 28, v92 bitop3:0x48
	v_bitop3_b32 v66, v92, v65, 28 bitop3:0x6c
	v_add_u32_e32 v68, 4, v65
	v_add_u32_e32 v69, 8, v65
	v_add_u32_e32 v70, 12, v65
	v_add_u32_e32 v71, 16, v65
	v_add_u32_e32 v72, 20, v65
	v_add_u32_e32 v73, 24, v65
	v_add_u32_e32 v65, 28, v65
	v_add_u32_e32 v141, 32, v131
	v_bitop3_b32 v74, v131, 28, v92 bitop3:0x48
	v_lshlrev_b32_e32 v76, 7, v147
	v_lshlrev_b32_e32 v75, 2, v75
	v_bitop3_b32 v68, v68, v92, 28 bitop3:0x78
	v_bitop3_b32 v69, v69, v92, 28 bitop3:0x78
	v_bitop3_b32 v70, v70, v92, 28 bitop3:0x78
	v_bitop3_b32 v71, v71, v92, 28 bitop3:0x78
	v_bitop3_b32 v72, v72, v92, 28 bitop3:0x78
	v_bitop3_b32 v73, v73, v92, 28 bitop3:0x78
	v_bitop3_b32 v65, v65, v92, 28 bitop3:0x78
	v_add3_u32 v148, s11, v76, v75
	v_lshlrev_b32_e32 v75, 7, v141
	v_lshlrev_b32_e32 v74, 2, v74
	v_lshl_add_u32 v66, v66, 2, s11
	v_lshlrev_b32_e32 v67, 7, v64
	v_lshl_add_u32 v68, v68, 2, s11
	v_lshl_add_u32 v69, v69, 2, s11
	v_lshl_add_u32 v70, v70, 2, s11
	v_lshl_add_u32 v71, v71, 2, s11
	v_lshl_add_u32 v72, v72, 2, s11
	v_lshl_add_u32 v73, v73, 2, s11
	v_lshl_add_u32 v65, v65, 2, s11
	v_add3_u32 v149, s11, v75, v74
	v_lshlrev_b32_e32 v75, 3, v142
	v_lshlrev_b32_e32 v128, 2, v64
	v_lshlrev_b32_e32 v64, 7, v131
	v_and_b32_e32 v130, 56, v75
	v_add3_u32 v142, s11, v64, v74
	s_lshl_b32 s70, s3, 4
	s_movk_i32 s71, 0x1400
	s_movk_i32 s72, 0x4c00
	v_add_u32_e32 v150, v66, v67
	v_add_u32_e32 v151, v68, v67
	v_add_u32_e32 v152, v69, v67
	v_add_u32_e32 v153, v70, v67
	v_add_u32_e32 v154, v71, v67
	v_add_u32_e32 v155, v72, v67
	v_add_u32_e32 v156, v73, v67
	v_add_u32_e32 v157, v65, v67
	s_branch .LBB8_111

.LBB8_140:
	s_lshl_b32 s16, s11, 6
	s_waitcnt vmcnt(1)
	v_add_u32_e32 v122, s16, v134
	s_waitcnt lgkmcnt(0)
	v_or_b32_e32 v66, 1, v122
	v_add_u32_e32 v72, 8, v122
	v_add_u32_e32 v74, 9, v122
	v_add_u32_e32 v80, 16, v122
	v_add_u32_e32 v82, 17, v122
	v_add_u32_e32 v88, 24, v122
	v_add_u32_e32 v90, 25, v122
	v_mad_i64_i32 v[64:65], s[76:77], s28, v122, 0
	s_ashr_i32 s57, s56, 31
	v_mad_i64_i32 v[66:67], s[76:77], s28, v66, 0
	v_mad_i64_i32 v[72:73], s[76:77], s28, v72, 0
	v_mad_i64_i32 v[74:75], s[76:77], s28, v74, 0
	v_mad_i64_i32 v[80:81], s[76:77], s28, v80, 0
	v_mad_i64_i32 v[82:83], s[76:77], s28, v82, 0
	v_mad_i64_i32 v[88:89], s[76:77], s28, v88, 0
	v_mad_i64_i32 v[90:91], s[76:77], s28, v90, 0
	v_lshl_add_u64 v[64:65], v[64:65], 2, s[54:55]
	s_lshl_b64 s[56:57], s[56:57], 2
	v_lshl_add_u64 v[66:67], v[66:67], 2, s[54:55]
	v_lshl_add_u64 v[72:73], v[72:73], 2, s[54:55]
	v_lshl_add_u64 v[74:75], v[74:75], 2, s[54:55]
	v_lshl_add_u64 v[80:81], v[80:81], 2, s[54:55]
	v_lshl_add_u64 v[82:83], v[82:83], 2, s[54:55]
	v_lshl_add_u64 v[88:89], v[88:89], 2, s[54:55]
	v_lshl_add_u64 v[90:91], v[90:91], 2, s[54:55]
	v_lshl_add_u64 v[64:65], v[64:65], 0, s[56:57]
	v_lshl_add_u64 v[66:67], v[66:67], 0, s[56:57]
	v_lshl_add_u64 v[72:73], v[72:73], 0, s[56:57]
	v_lshl_add_u64 v[74:75], v[74:75], 0, s[56:57]
	v_lshl_add_u64 v[80:81], v[80:81], 0, s[56:57]
	v_lshl_add_u64 v[82:83], v[82:83], 0, s[56:57]
	v_lshl_add_u64 v[88:89], v[88:89], 0, s[56:57]
	v_lshl_add_u64 v[90:91], v[90:91], 0, s[56:57]
	v_lshl_add_u64 v[64:65], v[64:65], 0, v[128:129]
	v_lshl_add_u64 v[68:69], v[66:67], 0, v[128:129]
	v_lshl_add_u64 v[72:73], v[72:73], 0, v[128:129]
	v_lshl_add_u64 v[76:77], v[74:75], 0, v[128:129]
	v_lshl_add_u64 v[80:81], v[80:81], 0, v[128:129]
	v_lshl_add_u64 v[84:85], v[82:83], 0, v[128:129]
	v_lshl_add_u64 v[88:89], v[88:89], 0, v[128:129]
	v_lshl_add_u64 v[92:93], v[90:91], 0, v[128:129]
	global_load_dwordx4 v[64:67], v[64:65], off nt
	s_nop 0
	global_load_dwordx4 v[68:71], v[68:69], off nt
	s_nop 0
	global_load_dwordx4 v[72:75], v[72:73], off nt
	s_nop 0
	global_load_dwordx4 v[76:79], v[76:77], off nt
	s_nop 0
	global_load_dwordx4 v[80:83], v[80:81], off nt
	s_nop 0
	global_load_dwordx4 v[84:87], v[84:85], off nt
	s_nop 0
	global_load_dwordx4 v[88:91], v[88:89], off nt
	s_nop 0
	global_load_dwordx4 v[96:99], v[92:93], off nt
	v_add_u32_e32 v92, 32, v122
	v_add_u32_e32 v94, 33, v122
	v_add_u32_e32 v104, 40, v122
	v_add_u32_e32 v106, 41, v122
	v_add_u32_e32 v112, 48, v122
	v_add_u32_e32 v114, 49, v122
	v_add_u32_e32 v120, 56, v122
	v_add_u32_e32 v122, 57, v122
	v_mad_i64_i32 v[92:93], s[76:77], s28, v92, 0
	v_mad_i64_i32 v[94:95], s[76:77], s28, v94, 0
	v_mad_i64_i32 v[104:105], s[76:77], s28, v104, 0
	v_mad_i64_i32 v[106:107], s[76:77], s28, v106, 0
	v_mad_i64_i32 v[112:113], s[76:77], s28, v112, 0
	v_mad_i64_i32 v[114:115], s[76:77], s28, v114, 0
	v_mad_i64_i32 v[120:121], s[76:77], s28, v120, 0
	v_mad_i64_i32 v[122:123], s[28:29], s28, v122, 0
	v_lshl_add_u64 v[92:93], v[92:93], 2, s[54:55]
	v_lshl_add_u64 v[94:95], v[94:95], 2, s[54:55]
	v_lshl_add_u64 v[104:105], v[104:105], 2, s[54:55]
	v_lshl_add_u64 v[106:107], v[106:107], 2, s[54:55]
	v_lshl_add_u64 v[112:113], v[112:113], 2, s[54:55]
	v_lshl_add_u64 v[114:115], v[114:115], 2, s[54:55]
	v_lshl_add_u64 v[120:121], v[120:121], 2, s[54:55]
	v_lshl_add_u64 v[122:123], v[122:123], 2, s[54:55]
	v_lshl_add_u64 v[92:93], v[92:93], 0, s[56:57]
	v_lshl_add_u64 v[94:95], v[94:95], 0, s[56:57]
	v_lshl_add_u64 v[104:105], v[104:105], 0, s[56:57]
	v_lshl_add_u64 v[106:107], v[106:107], 0, s[56:57]
	v_lshl_add_u64 v[112:113], v[112:113], 0, s[56:57]
	v_lshl_add_u64 v[114:115], v[114:115], 0, s[56:57]
	v_lshl_add_u64 v[120:121], v[120:121], 0, s[56:57]
	v_lshl_add_u64 v[122:123], v[122:123], 0, s[56:57]
	v_lshl_add_u64 v[92:93], v[92:93], 0, v[128:129]
	v_lshl_add_u64 v[100:101], v[94:95], 0, v[128:129]
	v_lshl_add_u64 v[104:105], v[104:105], 0, v[128:129]
	v_lshl_add_u64 v[108:109], v[106:107], 0, v[128:129]
	v_lshl_add_u64 v[112:113], v[112:113], 0, v[128:129]
	v_lshl_add_u64 v[116:117], v[114:115], 0, v[128:129]
	v_lshl_add_u64 v[120:121], v[120:121], 0, v[128:129]
	s_waitcnt vmcnt(8)
	v_lshl_add_u64 v[124:125], v[122:123], 0, v[128:129]
	global_load_dwordx4 v[92:95], v[92:93], off nt
	s_nop 0
	global_load_dwordx4 v[100:103], v[100:101], off nt
	s_nop 0
	global_load_dwordx4 v[104:107], v[104:105], off nt
	s_nop 0
	global_load_dwordx4 v[108:111], v[108:109], off nt
	s_nop 0
	global_load_dwordx4 v[112:115], v[112:113], off nt
	s_nop 0
	global_load_dwordx4 v[116:119], v[116:117], off nt
	s_nop 0
	global_load_dwordx4 v[120:123], v[120:121], off nt
	s_nop 0
	global_load_dwordx4 v[124:127], v[124:125], off nt
	s_waitcnt vmcnt(30)
	v_cvt_pk_bf16_f32 v0, v0, v4
	v_cvt_pk_bf16_f32 v1, v1, v5
	v_cvt_pk_bf16_f32 v2, v2, v6
	v_cvt_pk_bf16_f32 v3, v3, v7
	s_waitcnt vmcnt(28)
	v_cvt_pk_bf16_f32 v4, v8, v12
	v_cvt_pk_bf16_f32 v5, v9, v13
	v_cvt_pk_bf16_f32 v6, v10, v14
	v_cvt_pk_bf16_f32 v7, v11, v15
	s_waitcnt vmcnt(26)
	v_cvt_pk_bf16_f32 v8, v16, v20
	v_cvt_pk_bf16_f32 v9, v17, v21
	v_cvt_pk_bf16_f32 v10, v18, v22
	v_cvt_pk_bf16_f32 v11, v19, v23
	s_waitcnt vmcnt(24)
	v_cvt_pk_bf16_f32 v12, v24, v28
	v_cvt_pk_bf16_f32 v13, v25, v29
	v_cvt_pk_bf16_f32 v14, v26, v30
	v_cvt_pk_bf16_f32 v15, v27, v31
	s_waitcnt vmcnt(22)
	v_cvt_pk_bf16_f32 v16, v32, v36
	v_cvt_pk_bf16_f32 v17, v33, v37
	v_cvt_pk_bf16_f32 v18, v34, v38
	v_cvt_pk_bf16_f32 v19, v35, v39
	s_waitcnt vmcnt(20)
	v_cvt_pk_bf16_f32 v20, v40, v44
	v_cvt_pk_bf16_f32 v21, v41, v45
	v_cvt_pk_bf16_f32 v22, v42, v46
	v_cvt_pk_bf16_f32 v23, v43, v47
	s_waitcnt vmcnt(18)
	v_cvt_pk_bf16_f32 v24, v48, v52
	v_cvt_pk_bf16_f32 v25, v49, v53
	v_cvt_pk_bf16_f32 v26, v50, v54
	v_cvt_pk_bf16_f32 v27, v51, v55
	s_waitcnt vmcnt(16)
	v_cvt_pk_bf16_f32 v28, v56, v60
	v_cvt_pk_bf16_f32 v29, v57, v61
	v_cvt_pk_bf16_f32 v30, v58, v62
	v_cvt_pk_bf16_f32 v31, v59, v63
	ds_write2_b32 v150, v0, v1 offset1:32
	ds_write2_b32 v150, v2, v3 offset0:64 offset1:96
	ds_write2_b32 v151, v4, v5 offset1:32
	ds_write2_b32 v151, v6, v7 offset0:64 offset1:96
	ds_write2_b32 v152, v8, v9 offset1:32
	ds_write2_b32 v152, v10, v11 offset0:64 offset1:96
	ds_write2_b32 v153, v12, v13 offset1:32
	ds_write2_b32 v153, v14, v15 offset0:64 offset1:96
	ds_write2_b32 v154, v16, v17 offset1:32
	ds_write2_b32 v154, v18, v19 offset0:64 offset1:96
	ds_write2_b32 v155, v20, v21 offset1:32
	ds_write2_b32 v155, v22, v23 offset0:64 offset1:96
	ds_write2_b32 v156, v24, v25 offset1:32
	ds_write2_b32 v156, v26, v27 offset0:64 offset1:96
	ds_write2_b32 v157, v28, v29 offset1:32
	ds_write2_b32 v157, v30, v31 offset0:64 offset1:96
	s_waitcnt lgkmcnt(0)
	ds_read_b128 v[24:27], v136
	ds_read_b128 v[20:23], v138
	ds_read_b128 v[16:19], v140
	ds_read_b128 v[12:15], v149
	ds_read_b128 v[8:11], v144
	ds_read_b128 v[4:7], v146
	ds_read_b128 v[0:3], v148
	v_lshlrev_b32_e32 v28, 6, v132
	v_ashrrev_i32_e32 v29, 31, v28
	v_cmp_gt_i32_e32 vcc, s61, v131
	v_lshlrev_b32_e32 v132, 1, v130
	s_and_saveexec_b64 s[28:29], vcc
	s_cbranch_execnz .LBB8_155
	s_or_b64 exec, exec, s[28:29]
	v_cmp_gt_i32_e32 vcc, s61, v135
	s_and_saveexec_b64 s[28:29], vcc
	s_cbranch_execnz .LBB8_156

.LBB8_186:
	v_lshl_add_u32 v58, s54, 6, v134
	s_waitcnt lgkmcnt(0)
	v_mad_i64_i32 v[0:1], s[56:57], s28, v58, 0
	v_or_b32_e32 v2, 1, v58
	v_add_u32_e32 v8, 8, v58
	v_add_u32_e32 v10, 9, v58
	v_add_u32_e32 v16, 16, v58
	v_add_u32_e32 v18, 17, v58
	v_add_u32_e32 v24, 24, v58
	v_add_u32_e32 v26, 25, v58
	v_add_u32_e32 v32, 32, v58
	v_add_u32_e32 v34, 33, v58
	v_add_u32_e32 v40, 40, v58
	v_add_u32_e32 v42, 41, v58
	v_add_u32_e32 v48, 48, v58
	v_add_u32_e32 v50, 49, v58
	v_add_u32_e32 v56, 56, v58
	v_add_u32_e32 v58, 57, v58
	s_ashr_i32 s35, s34, 31
	v_mad_i64_i32 v[2:3], s[56:57], s28, v2, 0
	v_mad_i64_i32 v[8:9], s[56:57], s28, v8, 0
	v_mad_i64_i32 v[10:11], s[56:57], s28, v10, 0
	v_mad_i64_i32 v[16:17], s[56:57], s28, v16, 0
	v_mad_i64_i32 v[18:19], s[56:57], s28, v18, 0
	v_mad_i64_i32 v[24:25], s[56:57], s28, v24, 0
	v_mad_i64_i32 v[26:27], s[56:57], s28, v26, 0
	v_mad_i64_i32 v[32:33], s[56:57], s28, v32, 0
	v_mad_i64_i32 v[34:35], s[56:57], s28, v34, 0
	v_mad_i64_i32 v[40:41], s[56:57], s28, v40, 0
	v_mad_i64_i32 v[42:43], s[56:57], s28, v42, 0
	v_mad_i64_i32 v[48:49], s[56:57], s28, v48, 0
	v_mad_i64_i32 v[50:51], s[56:57], s28, v50, 0
	v_mad_i64_i32 v[56:57], s[56:57], s28, v56, 0
	v_mad_i64_i32 v[58:59], s[28:29], s28, v58, 0
	v_lshl_add_u64 v[0:1], v[0:1], 2, s[10:11]
	s_lshl_b64 s[34:35], s[34:35], 2
	v_lshl_add_u64 v[2:3], v[2:3], 2, s[10:11]
	v_lshl_add_u64 v[8:9], v[8:9], 2, s[10:11]
	v_lshl_add_u64 v[10:11], v[10:11], 2, s[10:11]
	v_lshl_add_u64 v[16:17], v[16:17], 2, s[10:11]
	v_lshl_add_u64 v[18:19], v[18:19], 2, s[10:11]
	v_lshl_add_u64 v[24:25], v[24:25], 2, s[10:11]
	v_lshl_add_u64 v[26:27], v[26:27], 2, s[10:11]
	v_lshl_add_u64 v[32:33], v[32:33], 2, s[10:11]
	v_lshl_add_u64 v[34:35], v[34:35], 2, s[10:11]
	v_lshl_add_u64 v[40:41], v[40:41], 2, s[10:11]
	v_lshl_add_u64 v[42:43], v[42:43], 2, s[10:11]
	v_lshl_add_u64 v[48:49], v[48:49], 2, s[10:11]
	v_lshl_add_u64 v[50:51], v[50:51], 2, s[10:11]
	v_lshl_add_u64 v[56:57], v[56:57], 2, s[10:11]
	v_lshl_add_u64 v[58:59], v[58:59], 2, s[10:11]
	v_lshl_add_u64 v[0:1], v[0:1], 0, s[34:35]
	v_lshl_add_u64 v[2:3], v[2:3], 0, s[34:35]
	v_lshl_add_u64 v[8:9], v[8:9], 0, s[34:35]
	v_lshl_add_u64 v[10:11], v[10:11], 0, s[34:35]
	v_lshl_add_u64 v[16:17], v[16:17], 0, s[34:35]
	v_lshl_add_u64 v[18:19], v[18:19], 0, s[34:35]
	v_lshl_add_u64 v[24:25], v[24:25], 0, s[34:35]
	v_lshl_add_u64 v[26:27], v[26:27], 0, s[34:35]
	v_lshl_add_u64 v[32:33], v[32:33], 0, s[34:35]
	v_lshl_add_u64 v[34:35], v[34:35], 0, s[34:35]
	v_lshl_add_u64 v[40:41], v[40:41], 0, s[34:35]
	v_lshl_add_u64 v[42:43], v[42:43], 0, s[34:35]
	v_lshl_add_u64 v[48:49], v[48:49], 0, s[34:35]
	v_lshl_add_u64 v[50:51], v[50:51], 0, s[34:35]
	v_lshl_add_u64 v[56:57], v[56:57], 0, s[34:35]
	v_lshl_add_u64 v[58:59], v[58:59], 0, s[34:35]
	v_lshl_add_u64 v[0:1], v[0:1], 0, v[128:129]
	v_lshl_add_u64 v[4:5], v[2:3], 0, v[128:129]
	v_lshl_add_u64 v[8:9], v[8:9], 0, v[128:129]
	v_lshl_add_u64 v[12:13], v[10:11], 0, v[128:129]
	v_lshl_add_u64 v[16:17], v[16:17], 0, v[128:129]
	v_lshl_add_u64 v[20:21], v[18:19], 0, v[128:129]
	v_lshl_add_u64 v[24:25], v[24:25], 0, v[128:129]
	v_lshl_add_u64 v[28:29], v[26:27], 0, v[128:129]
	v_lshl_add_u64 v[32:33], v[32:33], 0, v[128:129]
	v_lshl_add_u64 v[36:37], v[34:35], 0, v[128:129]
	v_lshl_add_u64 v[40:41], v[40:41], 0, v[128:129]
	v_lshl_add_u64 v[44:45], v[42:43], 0, v[128:129]
	v_lshl_add_u64 v[48:49], v[48:49], 0, v[128:129]
	v_lshl_add_u64 v[52:53], v[50:51], 0, v[128:129]
	v_lshl_add_u64 v[56:57], v[56:57], 0, v[128:129]
	v_lshl_add_u64 v[60:61], v[58:59], 0, v[128:129]
	global_load_dwordx4 v[0:3], v[0:1], off nt
	s_nop 0
	global_load_dwordx4 v[4:7], v[4:5], off nt
	s_nop 0
	global_load_dwordx4 v[8:11], v[8:9], off nt
	s_nop 0
	global_load_dwordx4 v[12:15], v[12:13], off nt
	s_nop 0
	global_load_dwordx4 v[16:19], v[16:17], off nt
	s_nop 0
	global_load_dwordx4 v[20:23], v[20:21], off nt
	s_nop 0
	global_load_dwordx4 v[24:27], v[24:25], off nt
	s_nop 0
	global_load_dwordx4 v[28:31], v[28:29], off nt
	s_nop 0
	global_load_dwordx4 v[32:35], v[32:33], off nt
	s_nop 0
	global_load_dwordx4 v[36:39], v[36:37], off nt
	s_nop 0
	global_load_dwordx4 v[40:43], v[40:41], off nt
	s_nop 0
	global_load_dwordx4 v[44:47], v[44:45], off nt
	s_nop 0
	global_load_dwordx4 v[48:51], v[48:49], off nt
	s_nop 0
	global_load_dwordx4 v[52:55], v[52:53], off nt
	s_nop 0
	global_load_dwordx4 v[56:59], v[56:57], off nt
	s_nop 0
	global_load_dwordx4 v[60:63], v[60:61], off nt
	s_waitcnt vmcnt(30)
	v_cvt_pk_bf16_f32 v64, v64, v68
	v_cvt_pk_bf16_f32 v65, v65, v69
	ds_write2_b32 v150, v64, v65 offset1:32
	v_cvt_pk_bf16_f32 v64, v66, v70
	v_cvt_pk_bf16_f32 v65, v67, v71
	ds_write2_b32 v150, v64, v65 offset0:64 offset1:96
	s_waitcnt vmcnt(28)
	v_cvt_pk_bf16_f32 v64, v72, v76
	v_cvt_pk_bf16_f32 v65, v73, v77
	ds_write2_b32 v151, v64, v65 offset1:32
	v_cvt_pk_bf16_f32 v64, v74, v78
	v_cvt_pk_bf16_f32 v65, v75, v79
	ds_write2_b32 v151, v64, v65 offset0:64 offset1:96
	s_waitcnt vmcnt(26)
	v_cvt_pk_bf16_f32 v64, v80, v84
	v_cvt_pk_bf16_f32 v65, v81, v85
	ds_write2_b32 v152, v64, v65 offset1:32
	v_cvt_pk_bf16_f32 v64, v82, v86
	v_cvt_pk_bf16_f32 v65, v83, v87
	ds_write2_b32 v152, v64, v65 offset0:64 offset1:96
	s_waitcnt vmcnt(24)
	v_cvt_pk_bf16_f32 v64, v88, v96
	v_cvt_pk_bf16_f32 v65, v89, v97
	ds_write2_b32 v153, v64, v65 offset1:32
	v_cvt_pk_bf16_f32 v64, v90, v98
	v_cvt_pk_bf16_f32 v65, v91, v99
	ds_write2_b32 v153, v64, v65 offset0:64 offset1:96
	s_waitcnt vmcnt(22)
	v_cvt_pk_bf16_f32 v64, v92, v100
	v_cvt_pk_bf16_f32 v65, v93, v101
	ds_write2_b32 v154, v64, v65 offset1:32
	v_cvt_pk_bf16_f32 v64, v94, v102
	v_cvt_pk_bf16_f32 v65, v95, v103
	ds_write2_b32 v154, v64, v65 offset0:64 offset1:96
	s_waitcnt vmcnt(20)
	v_cvt_pk_bf16_f32 v64, v104, v108
	v_cvt_pk_bf16_f32 v65, v105, v109
	ds_write2_b32 v155, v64, v65 offset1:32
	v_cvt_pk_bf16_f32 v64, v106, v110
	v_cvt_pk_bf16_f32 v65, v107, v111
	ds_write2_b32 v155, v64, v65 offset0:64 offset1:96
	s_waitcnt vmcnt(18)
	v_cvt_pk_bf16_f32 v64, v112, v116
	v_cvt_pk_bf16_f32 v65, v113, v117
	ds_write2_b32 v156, v64, v65 offset1:32
	v_cvt_pk_bf16_f32 v64, v114, v118
	v_cvt_pk_bf16_f32 v65, v115, v119
	ds_write2_b32 v156, v64, v65 offset0:64 offset1:96
	s_waitcnt vmcnt(16)
	v_cvt_pk_bf16_f32 v64, v120, v124
	v_cvt_pk_bf16_f32 v65, v121, v125
	ds_write2_b32 v157, v64, v65 offset1:32
	v_cvt_pk_bf16_f32 v64, v122, v126
	v_cvt_pk_bf16_f32 v65, v123, v127
	ds_write2_b32 v157, v64, v65 offset0:64 offset1:96
	s_waitcnt lgkmcnt(0)
	ds_read_b128 v[88:91], v136
	ds_read_b128 v[84:87], v138
	ds_read_b128 v[80:83], v140
	ds_read_b128 v[76:79], v149
	ds_read_b128 v[72:75], v144
	ds_read_b128 v[68:71], v146
	ds_read_b128 v[64:67], v148
	s_ashr_i32 s17, s16, 31
	v_cmp_gt_i32_e32 vcc, s75, v131
	s_and_saveexec_b64 s[10:11], vcc
	s_cbranch_execnz .LBB8_194
	s_or_b64 exec, exec, s[10:11]
	v_cmp_gt_i32_e32 vcc, s75, v135
	s_and_saveexec_b64 s[10:11], vcc
	s_cbranch_execnz .LBB8_195
